# residual-epilogue GEMM phases (P6,P9,P14,P17): workgroups with blockIdx bit 3 start ~12 us late (3x s_sleep 127) to de-phase the chip-wide residual read/write bursts
# baseline (speedup 1.0000x reference)
; #define WSBASE() const AS4 unsigned char* kp_ = (const AS4 unsigned char*)__builtin_amdgcn_kernarg_segment_ptr(); asm volatile("" : "+s"(kp_)); \
;                  unsigned char* wsb = *(unsigned char* const AS4*)(kp_ + 176); float* outp = *(float* const AS4*)(kp_ + 168); (void)outp; (void)wsb
; #define GRID_BAR() do { WSBASE(); XcdBarrier bar_; bar_.bar = (unsigned*)(wsb + WS_CTL) + CW_BAR; bar_.x = xb_xcc_id(); bar_.st = MISC + 8; xcd_barrier(bar_, wave == 0 && lane_id() == 0); } while (0)
; #define GRID_BAR() do {} while (0)
; #define BOTH(k) (IN(k) && IN((k) + 1))
; __global__ void __launch_bounds__(NTHR, 2) mega_fwd(Args) {
;     ...
;     for (int rep_ = 0; rep_ < NREP(6); ++rep_) if (IN(6)) {
;         WSBASE();
;         pg8::Gemm g{WSP(bf16_t, WS_CONCAT), WSP(bf16_t, WS_W_OUT0), DM, 64, DM, pg8::BK * 2, 0, 32768, (size_t)BM_ * DM * 2}; pg8::StaticOrder S; S.init(MTOK, DM, G, bx);
;         pg8::EpiResLN<2, false> E{nullptr, WSP(bf16_t, WS_XB), nullptr, nullptr, 0, nullptr, nullptr, WSP(f32x2, WS_PS)};
;         pg8::gemm_phase<pg8::EpiResLN<2, false>, pg8::StaticOrder, true>(lds, g, S, E, wave);
;         if (BOTH(6)) GRID_BAR();
.LBB0_562:
	s_bitcmp1_b32 s2, 3
	s_cbranch_scc0 .Lstagger_562
	s_sleep 127
	s_sleep 127
	s_sleep 127
